# dwconv LayerNorm: wave all-reduces via DPP row ops + permlane16/32 swaps instead of six ds_bpermute hops (bitwise-identical pairing)
# speedup vs baseline: 1.0185x; 1.0022x over previous
.LBB0_719:
	s_barrier
	ds_write2st64_b64 v190, v[152:153], v[154:155] offset1:8
	ds_write2st64_b64 v190, v[156:157], v[158:159] offset0:16 offset1:24
	ds_write2st64_b64 v190, v[160:161], v[162:163] offset0:32 offset1:40
	ds_write2st64_b64 v190, v[164:165], v[166:167] offset0:48 offset1:56
	ds_write2st64_b64 v190, v[168:169], v[170:171] offset0:64 offset1:72
	ds_write2st64_b64 v190, v[172:173], v[174:175] offset0:80 offset1:88
	ds_write2st64_b64 v190, v[176:177], v[178:179] offset0:96 offset1:104
	ds_write2st64_b64 v190, v[180:181], v[182:183] offset0:112 offset1:120
	ds_write_b64 v198, v[150:151]
	ds_write_b64 v199, v[148:149]
	ds_write_b64 v200, v[146:147]
	ds_write_b64 v201, v[144:145]
	ds_write_b64 v202, v[142:143]
	ds_write_b64 v203, v[140:141]
	ds_write_b64 v204, v[138:139]
	ds_write_b64 v205, v[136:137]
	ds_write_b64 v206, v[134:135]
	ds_write_b64 v207, v[132:133]
	ds_write_b64 v208, v[130:131]
	ds_write_b64 v209, v[128:129]
	ds_write_b64 v210, v[126:127]
	ds_write_b64 v211, v[124:125]
	ds_write_b64 v212, v[122:123]
	ds_write_b64 v213, v[120:121]
	s_waitcnt lgkmcnt(0)
	s_barrier
	ds_read_b128 v[8:11], v217
	ds_read_b128 v[20:23], v217 offset:1024
	ds_read_b128 v[16:19], v217 offset:2048
	ds_read_b128 v[34:37], v217 offset:3072
	v_mov_b32_e32 v226, 0x3727c5ac
	s_waitcnt lgkmcnt(3)
	v_mov_b32_e32 v2, v9
	v_mov_b32_e32 v3, v10
	v_mov_b32_e32 v4, v8
	v_mov_b32_e32 v5, v11
	v_pk_add_f32 v[2:3], v[2:3], v[4:5]
	s_waitcnt lgkmcnt(2)
	v_mov_b32_e32 v4, v21
	v_mov_b32_e32 v5, v22
	v_mov_b32_e32 v6, v20
	v_mov_b32_e32 v7, v23
	v_pk_add_f32 v[4:5], v[4:5], v[6:7]
	v_add_f32_e32 v0, v2, v3
	v_pk_add_f32 v[4:5], v[4:5], v[4:5] op_sel:[0,1] op_sel_hi:[1,0]
	v_add_f32_e32 v2, 0, v0
	s_waitcnt lgkmcnt(1)
	v_add_f32_e32 v6, v16, v17
	v_add_f32_e32 v12, v18, v19
	s_waitcnt lgkmcnt(0)
	v_mov_b32_e32 v3, v34
	v_mov_b32_e32 v5, v35
	v_mov_b32_e32 v7, v36
	v_mov_b32_e32 v13, v37
	v_pk_add_f32 v[2:3], v[2:3], v[4:5]
	v_pk_add_f32 v[4:5], v[6:7], v[12:13]
	s_nop 0
	v_pk_add_f32 v[2:3], v[2:3], v[4:5]
	s_nop 0
	v_add_f32_e32 v0, v2, v3
	s_nop 1
	v_add_f32_dpp v2, v0, v0 quad_perm:[1,0,3,2] row_mask:0xf bank_mask:0xf
	s_nop 1
	v_add_f32_dpp v0, v2, v2 quad_perm:[2,3,0,1] row_mask:0xf bank_mask:0xf
	s_nop 1
	v_add_f32_dpp v2, v0, v0 row_half_mirror row_mask:0xf bank_mask:0xf
	s_nop 1
	v_add_f32_dpp v0, v2, v2 row_ror:8 row_mask:0xf bank_mask:0xf
	v_mov_b32_e32 v2, v0
	s_nop 1
	v_permlane16_swap_b32_e32 v2, v0
	v_add_f32_e32 v0, v2, v0
	v_mov_b32_e32 v2, v0
	s_nop 1
	v_permlane32_swap_b32_e32 v2, v0
	v_add_f32_e32 v14, v2, v0
	v_fmamk_f32 v13, v14, 0xba800000, v9
	v_fmamk_f32 v12, v14, 0xba800000, v8
	v_fmamk_f32 v11, v14, 0xba800000, v11
	v_fmac_f32_e32 v10, 0xba800000, v14
	v_pk_mul_f32 v[2:3], v[10:11], v[10:11]
	v_pk_mul_f32 v[4:5], v[12:13], v[12:13]
	v_fmamk_f32 v25, v14, 0xba800000, v21
	v_pk_mov_b32 v[6:7], v[4:5], v[2:3] op_sel:[1,0]
	v_mov_b32_e32 v5, v3
	v_fmamk_f32 v24, v14, 0xba800000, v20
	v_fmamk_f32 v23, v14, 0xba800000, v23
	v_fmac_f32_e32 v22, 0xba800000, v14
	v_pk_add_f32 v[2:3], v[6:7], v[4:5]
	v_pk_mul_f32 v[4:5], v[22:23], v[22:23]
	v_pk_mul_f32 v[6:7], v[24:25], v[24:25]
	v_fmamk_f32 v20, v14, 0xba800000, v16
	v_pk_mov_b32 v[8:9], v[6:7], v[4:5] op_sel:[1,0]
	v_mov_b32_e32 v7, v5
	v_fmamk_f32 v21, v14, 0xba800000, v17
	v_fmac_f32_e32 v18, 0xba800000, v14
	v_mul_f32_e32 v0, v20, v20
	v_pk_add_f32 v[4:5], v[8:9], v[6:7]
	v_fmamk_f32 v19, v14, 0xba800000, v19
	v_pk_fma_f32 v[6:7], v[20:21], v[20:21], v[0:1] op_sel_hi:[1,1,0]
	v_mul_f32_e32 v0, v18, v18
	v_pk_add_f32 v[2:3], v[2:3], v[2:3] op_sel_hi:[0,1]
	v_pk_add_f32 v[4:5], v[4:5], v[4:5] op_sel_hi:[0,1]
	v_pk_fma_f32 v[8:9], v[18:19], v[18:19], v[0:1] op_sel_hi:[1,1,0]
	v_fmamk_f32 v37, v14, 0xba800000, v37
	v_fmamk_f32 v36, v14, 0xba800000, v36
	v_fmamk_f32 v35, v14, 0xba800000, v35
	v_fmac_f32_e32 v34, 0xba800000, v14
	v_mul_f32_e32 v6, v34, v34
	v_mul_f32_e32 v8, v35, v35
	v_mul_f32_e32 v2, v36, v36
	v_mul_f32_e32 v4, v37, v37
	v_pk_add_f32 v[6:7], v[6:7], v[8:9]
	v_pk_add_f32 v[2:3], v[2:3], v[4:5]
	s_nop 0
	v_pk_add_f32 v[2:3], v[6:7], v[2:3]
	s_nop 0
	v_add_f32_e32 v0, v2, v3
	s_nop 1
	v_add_f32_dpp v2, v0, v0 quad_perm:[1,0,3,2] row_mask:0xf bank_mask:0xf
	s_nop 1
	v_add_f32_dpp v0, v2, v2 quad_perm:[2,3,0,1] row_mask:0xf bank_mask:0xf
	s_nop 1
	v_add_f32_dpp v2, v0, v0 row_half_mirror row_mask:0xf bank_mask:0xf
	s_nop 1
	v_add_f32_dpp v0, v2, v2 row_ror:8 row_mask:0xf bank_mask:0xf
	v_mov_b32_e32 v2, v0
	s_nop 1
	v_permlane16_swap_b32_e32 v2, v0
	v_add_f32_e32 v0, v2, v0
	v_mov_b32_e32 v2, v0
	s_nop 1
	v_permlane32_swap_b32_e32 v2, v0
	v_add_f32_e32 v0, v2, v0
	v_fmamk_f32 v0, v0, 0x3a800000, v226
	v_cmp_gt_f32_e32 vcc, s31, v0
	v_mul_f32_e32 v2, 0x4f800000, v0
	s_nop 0
	v_cndmask_b32_e32 v0, v0, v2, vcc
	v_sqrt_f32_e32 v2, v0
	s_nop 0
	v_add_u32_e32 v3, -1, v2
	v_fma_f32 v4, -v3, v2, v0
	v_cmp_ge_f32_e64 s[42:43], 0, v4
	v_add_u32_e32 v4, 1, v2
	s_nop 0
	v_cndmask_b32_e64 v3, v2, v3, s[42:43]
	v_fma_f32 v2, -v4, v2, v0
	v_cmp_lt_f32_e64 s[42:43], 0, v2
	s_nop 1
	v_cndmask_b32_e64 v2, v3, v4, s[42:43]
	v_mul_f32_e32 v3, 0x37800000, v2
	v_cndmask_b32_e32 v2, v2, v3, vcc
	v_cmp_class_f32_e32 vcc, v0, v241
	s_nop 1
	v_cndmask_b32_e32 v0, v2, v0, vcc
	v_div_scale_f32 v2, s[0:1], v0, v0, 1.0
	v_rcp_f32_e32 v3, v2
	s_nop 0
	v_fma_f32 v4, -v2, v3, 1.0
	v_fmac_f32_e32 v3, v4, v3
	v_div_scale_f32 v4, vcc, 1.0, v0, 1.0
	v_mul_f32_e32 v5, v4, v3
	v_fma_f32 v6, -v2, v5, v4
	v_fmac_f32_e32 v5, v6, v3
	v_fma_f32 v2, -v2, v5, v4
	v_div_fmas_f32 v2, v2, v3, v5
	v_div_fixup_f32 v0, v2, v0, 1.0
	v_add_u32_e32 v2, s9, v191
	v_ashrrev_i32_e32 v3, 31, v2
	v_lshlrev_b64 v[14:15], 11, v[2:3]
	global_load_dwordx4 v[2:5], v[114:115], off
	global_load_dwordx4 v[6:9], v[116:117], off
	v_pk_mul_f32 v[12:13], v[12:13], v[0:1] op_sel_hi:[1,0]
	v_pk_mul_f32 v[10:11], v[10:11], v[0:1] op_sel_hi:[1,0]
	v_lshl_add_u64 v[38:39], v[118:119], 0, v[14:15]
	v_pk_mul_f32 v[24:25], v[24:25], v[0:1] op_sel_hi:[1,0]
	v_pk_mul_f32 v[22:23], v[22:23], v[0:1] op_sel_hi:[1,0]
	v_pk_mul_f32 v[20:21], v[20:21], v[0:1] op_sel_hi:[1,0]
	v_pk_mul_f32 v[18:19], v[18:19], v[0:1] op_sel_hi:[1,0]
	v_pk_mul_f32 v[34:35], v[34:35], v[0:1] op_sel_hi:[1,0]
	v_pk_mul_f32 v[36:37], v[36:37], v[0:1] op_sel_hi:[1,0]
	s_waitcnt vmcnt(0)
	v_pk_fma_f32 v[12:13], v[2:3], v[12:13], v[6:7]
	s_nop 0
	v_mul_f32_e32 v16, 0xbfb8aa3b, v12
	v_mul_f32_e32 v17, 0xbfb8aa3b, v13
	v_exp_f32_e32 v16, v16
	v_exp_f32_e32 v17, v17
	v_pk_fma_f32 v[10:11], v[4:5], v[10:11], v[8:9]
	v_add_f32_e32 v16, 1.0, v16
	v_add_f32_e32 v17, 1.0, v17
	v_rcp_f32_e32 v16, v16
	v_rcp_f32_e32 v17, v17
	s_nop 0
	v_pk_mul_f32 v[12:13], v[12:13], v[16:17]
	v_mul_f32_e32 v16, 0xbfb8aa3b, v10
	v_mul_f32_e32 v17, 0xbfb8aa3b, v11
	v_exp_f32_e32 v16, v16
	v_exp_f32_e32 v17, v17
	v_cvt_pk_bf16_f32 v12, v12, v13
	v_add_f32_e32 v16, 1.0, v16
	v_add_f32_e32 v17, 1.0, v17
	v_rcp_f32_e32 v16, v16
	v_rcp_f32_e32 v17, v17
	s_nop 0
	v_pk_mul_f32 v[10:11], v[10:11], v[16:17]
	s_nop 0
	v_cvt_pk_bf16_f32 v13, v10, v11
	global_store_dwordx2 v[38:39], v[12:13], off
	global_load_dwordx4 v[10:13], v[114:115], off offset:1024
	s_nop 0
	global_load_dwordx4 v[14:17], v[116:117], off offset:1024
	s_waitcnt vmcnt(0)
	v_pk_fma_f32 v[24:25], v[10:11], v[24:25], v[14:15]
	s_nop 0
	v_mul_f32_e32 v26, 0xbfb8aa3b, v24
	v_mul_f32_e32 v27, 0xbfb8aa3b, v25
	v_exp_f32_e32 v26, v26
	v_exp_f32_e32 v27, v27
	v_pk_fma_f32 v[22:23], v[12:13], v[22:23], v[16:17]
	v_add_f32_e32 v26, 1.0, v26
	v_add_f32_e32 v27, 1.0, v27
	v_rcp_f32_e32 v26, v26
	v_rcp_f32_e32 v27, v27
	s_nop 0
	v_pk_mul_f32 v[24:25], v[24:25], v[26:27]
	v_mul_f32_e32 v26, 0xbfb8aa3b, v22
	v_mul_f32_e32 v27, 0xbfb8aa3b, v23
	v_exp_f32_e32 v26, v26
	v_exp_f32_e32 v27, v27
	v_cvt_pk_bf16_f32 v24, v24, v25
	v_add_f32_e32 v26, 1.0, v26
	v_add_f32_e32 v27, 1.0, v27
	v_rcp_f32_e32 v26, v26
	v_rcp_f32_e32 v27, v27
	s_nop 0
	v_pk_mul_f32 v[22:23], v[22:23], v[26:27]
	s_nop 0
	v_cvt_pk_bf16_f32 v25, v22, v23
	global_store_dwordx2 v[38:39], v[24:25], off offset:512
	global_load_dwordx4 v[26:29], v[114:115], off offset:2048
	global_load_dwordx4 v[30:33], v[116:117], off offset:2048
	s_waitcnt vmcnt(0)
	v_pk_fma_f32 v[20:21], v[26:27], v[20:21], v[30:31]
	s_nop 0
	v_mul_f32_e32 v22, 0xbfb8aa3b, v20
	v_mul_f32_e32 v23, 0xbfb8aa3b, v21
	v_exp_f32_e32 v22, v22
	v_exp_f32_e32 v23, v23
	v_pk_fma_f32 v[18:19], v[28:29], v[18:19], v[32:33]
	v_add_f32_e32 v22, 1.0, v22
	v_add_f32_e32 v23, 1.0, v23
	v_rcp_f32_e32 v22, v22
	v_rcp_f32_e32 v23, v23
	s_nop 0
	v_pk_mul_f32 v[20:21], v[20:21], v[22:23]
	v_mul_f32_e32 v22, 0xbfb8aa3b, v18
	v_mul_f32_e32 v23, 0xbfb8aa3b, v19
	v_exp_f32_e32 v22, v22
	v_exp_f32_e32 v23, v23
	v_cvt_pk_bf16_f32 v20, v20, v21
	v_add_f32_e32 v22, 1.0, v22
	v_add_f32_e32 v23, 1.0, v23
	v_rcp_f32_e32 v22, v22
	v_rcp_f32_e32 v23, v23
	s_nop 0
	v_pk_mul_f32 v[18:19], v[18:19], v[22:23]
	s_nop 0
	v_cvt_pk_bf16_f32 v21, v18, v19
	global_store_dwordx2 v[38:39], v[20:21], off offset:1024
	global_load_dwordx4 v[18:21], v[114:115], off offset:3072
	s_nop 0
	global_load_dwordx4 v[22:25], v[116:117], off offset:3072
	ds_read_b128 v[46:49], v218
	ds_read_b128 v[42:45], v218 offset:1024
	s_waitcnt vmcnt(0)
	v_pk_fma_f32 v[34:35], v[18:19], v[34:35], v[22:23]
	s_nop 0
	v_mul_f32_e32 v0, 0xbfb8aa3b, v34
	v_exp_f32_e32 v0, v0
	v_pk_fma_f32 v[36:37], v[20:21], v[36:37], v[24:25]
	v_add_f32_e32 v0, 1.0, v0
	v_rcp_f32_e32 v40, v0
	v_mul_f32_e32 v0, 0xbfb8aa3b, v35
	v_exp_f32_e32 v0, v0
	s_nop 0
	v_add_f32_e32 v0, 1.0, v0
	v_rcp_f32_e32 v41, v0
	v_mul_f32_e32 v0, 0xbfb8aa3b, v36
	v_exp_f32_e32 v0, v0
	v_pk_mul_f32 v[34:35], v[34:35], v[40:41]
	s_nop 0
	v_cvt_pk_bf16_f32 v34, v34, v35
	v_add_f32_e32 v0, 1.0, v0
	v_rcp_f32_e32 v40, v0
	v_mul_f32_e32 v0, 0xbfb8aa3b, v37
	v_exp_f32_e32 v0, v0
	s_nop 0
	v_add_f32_e32 v0, 1.0, v0
	v_rcp_f32_e32 v41, v0
	s_nop 0
	v_pk_mul_f32 v[36:37], v[36:37], v[40:41]
	s_nop 0
	v_cvt_pk_bf16_f32 v35, v36, v37
	global_store_dwordx2 v[38:39], v[34:35], off offset:1536
	s_waitcnt lgkmcnt(1)
	v_mov_b32_e32 v34, v47
	v_mov_b32_e32 v35, v48
	v_mov_b32_e32 v36, v46
	v_mov_b32_e32 v37, v49
	v_pk_add_f32 v[34:35], v[34:35], v[36:37]
	s_waitcnt lgkmcnt(0)
	v_mov_b32_e32 v36, v42
	v_add_f32_e32 v0, v34, v35
	v_mov_b32_e32 v34, v43
	v_mov_b32_e32 v35, v44
	v_mov_b32_e32 v37, v45
	v_pk_add_f32 v[34:35], v[34:35], v[36:37]
	ds_read_b128 v[38:41], v218 offset:2048
	v_pk_add_f32 v[186:187], v[34:35], v[34:35] op_sel:[0,1] op_sel_hi:[1,0]
	ds_read_b128 v[34:37], v218 offset:3072
	v_add_f32_e32 v184, 0, v0
	s_waitcnt lgkmcnt(1)
	v_add_f32_e32 v222, v38, v39
	v_add_f32_e32 v224, v40, v41
	s_waitcnt lgkmcnt(0)
	v_mov_b32_e32 v185, v34
	v_mov_b32_e32 v187, v35
	v_mov_b32_e32 v223, v36
	v_mov_b32_e32 v225, v37
	v_pk_add_f32 v[184:185], v[184:185], v[186:187]
	v_pk_add_f32 v[186:187], v[222:223], v[224:225]
	s_nop 0
	v_pk_add_f32 v[184:185], v[184:185], v[186:187]
	s_nop 0
	v_add_f32_e32 v0, v184, v185
	s_nop 1
	v_add_f32_dpp v184, v0, v0 quad_perm:[1,0,3,2] row_mask:0xf bank_mask:0xf
	s_nop 1
	v_add_f32_dpp v0, v184, v184 quad_perm:[2,3,0,1] row_mask:0xf bank_mask:0xf
	s_nop 1
	v_add_f32_dpp v184, v0, v0 row_half_mirror row_mask:0xf bank_mask:0xf
	s_nop 1
	v_add_f32_dpp v0, v184, v184 row_ror:8 row_mask:0xf bank_mask:0xf
	v_mov_b32_e32 v184, v0
	s_nop 1
	v_permlane16_swap_b32_e32 v184, v0
	v_add_f32_e32 v0, v184, v0
	v_mov_b32_e32 v184, v0
	s_nop 1
	v_permlane32_swap_b32_e32 v184, v0
	v_add_f32_e32 v221, v184, v0
	v_fmamk_f32 v47, v221, 0xba800000, v47
	v_fmamk_f32 v46, v221, 0xba800000, v46
	v_fmamk_f32 v49, v221, 0xba800000, v49
	v_fmac_f32_e32 v48, 0xba800000, v221
	v_pk_mul_f32 v[184:185], v[48:49], v[48:49]
	v_pk_mul_f32 v[186:187], v[46:47], v[46:47]
	v_fmamk_f32 v43, v221, 0xba800000, v43
	v_pk_mov_b32 v[222:223], v[186:187], v[184:185] op_sel:[1,0]
	v_mov_b32_e32 v187, v185
	v_fmamk_f32 v42, v221, 0xba800000, v42
	v_fmamk_f32 v45, v221, 0xba800000, v45
	v_fmac_f32_e32 v44, 0xba800000, v221
	v_pk_add_f32 v[184:185], v[222:223], v[186:187]
	v_pk_mul_f32 v[186:187], v[44:45], v[44:45]
	v_pk_mul_f32 v[222:223], v[42:43], v[42:43]
	v_fmamk_f32 v38, v221, 0xba800000, v38
	v_pk_mov_b32 v[224:225], v[222:223], v[186:187] op_sel:[1,0]
	v_mov_b32_e32 v223, v187
	v_fmamk_f32 v39, v221, 0xba800000, v39
	v_fmac_f32_e32 v40, 0xba800000, v221
	v_mul_f32_e32 v0, v38, v38
	v_pk_add_f32 v[186:187], v[224:225], v[222:223]
	v_fmamk_f32 v41, v221, 0xba800000, v41
	v_pk_fma_f32 v[222:223], v[38:39], v[38:39], v[0:1] op_sel_hi:[1,1,0]
	v_mul_f32_e32 v0, v40, v40
	v_pk_add_f32 v[184:185], v[184:185], v[184:185] op_sel_hi:[0,1]
	v_pk_add_f32 v[186:187], v[186:187], v[186:187] op_sel_hi:[0,1]
	v_pk_fma_f32 v[224:225], v[40:41], v[40:41], v[0:1] op_sel_hi:[1,1,0]
	v_fmamk_f32 v37, v221, 0xba800000, v37
	v_fmamk_f32 v36, v221, 0xba800000, v36
	v_fmamk_f32 v35, v221, 0xba800000, v35
	v_fmac_f32_e32 v34, 0xba800000, v221
	v_mul_f32_e32 v222, v34, v34
	v_mul_f32_e32 v224, v35, v35
	v_mul_f32_e32 v184, v36, v36
	v_mul_f32_e32 v186, v37, v37
	v_pk_add_f32 v[222:223], v[222:223], v[224:225]
	v_pk_add_f32 v[184:185], v[184:185], v[186:187]
	s_nop 0
	v_pk_add_f32 v[184:185], v[222:223], v[184:185]
	s_nop 0
	v_add_f32_e32 v0, v184, v185
	s_nop 1
	v_add_f32_dpp v184, v0, v0 quad_perm:[1,0,3,2] row_mask:0xf bank_mask:0xf
	s_nop 1
	v_add_f32_dpp v0, v184, v184 quad_perm:[2,3,0,1] row_mask:0xf bank_mask:0xf
	s_nop 1
	v_add_f32_dpp v184, v0, v0 row_half_mirror row_mask:0xf bank_mask:0xf
	s_nop 1
	v_add_f32_dpp v0, v184, v184 row_ror:8 row_mask:0xf bank_mask:0xf
	v_mov_b32_e32 v184, v0
	s_nop 1
	v_permlane16_swap_b32_e32 v184, v0
	v_add_f32_e32 v0, v184, v0
	v_mov_b32_e32 v184, v0
	s_nop 1
	v_permlane32_swap_b32_e32 v184, v0
	v_add_f32_e32 v0, v184, v0
	v_fmamk_f32 v0, v0, 0x3a800000, v226
	v_cmp_gt_f32_e32 vcc, s31, v0
	v_mul_f32_e32 v184, 0x4f800000, v0
	s_nop 0
	v_cndmask_b32_e32 v0, v0, v184, vcc
	v_sqrt_f32_e32 v184, v0
	s_nop 0
	v_add_u32_e32 v185, -1, v184
	v_fma_f32 v186, -v185, v184, v0
	v_cmp_ge_f32_e64 s[42:43], 0, v186
	v_add_u32_e32 v186, 1, v184
	s_nop 0
	v_cndmask_b32_e64 v185, v184, v185, s[42:43]
	v_fma_f32 v184, -v186, v184, v0
	v_cmp_lt_f32_e64 s[42:43], 0, v184
	s_nop 1
	v_cndmask_b32_e64 v184, v185, v186, s[42:43]
	v_mul_f32_e32 v185, 0x37800000, v184
	v_cndmask_b32_e32 v184, v184, v185, vcc
	v_cmp_class_f32_e32 vcc, v0, v241
	s_nop 1
	v_cndmask_b32_e32 v0, v184, v0, vcc
	v_div_scale_f32 v184, s[0:1], v0, v0, 1.0
	v_rcp_f32_e32 v185, v184
	s_nop 0
	v_fma_f32 v186, -v184, v185, 1.0
	v_fmac_f32_e32 v185, v186, v185
	v_div_scale_f32 v186, vcc, 1.0, v0, 1.0
	v_mul_f32_e32 v187, v186, v185
	v_fma_f32 v221, -v184, v187, v186
	v_fmac_f32_e32 v187, v221, v185
	v_fma_f32 v184, -v184, v187, v186
	v_div_fmas_f32 v184, v184, v185, v187
	v_div_fixup_f32 v0, v184, v0, 1.0
	v_pk_mul_f32 v[46:47], v[46:47], v[0:1] op_sel_hi:[1,0]
	v_pk_mul_f32 v[48:49], v[48:49], v[0:1] op_sel_hi:[1,0]
	v_pk_fma_f32 v[46:47], v[2:3], v[46:47], v[6:7]
	v_pk_fma_f32 v[48:49], v[4:5], v[48:49], v[8:9]
	v_mul_f32_e32 v186, 0xbfb8aa3b, v46
	v_mul_f32_e32 v187, 0xbfb8aa3b, v47
	v_exp_f32_e32 v186, v186
	v_exp_f32_e32 v187, v187
	v_add_u32_e32 v184, s9, v214
	v_ashrrev_i32_e32 v185, 31, v184
	v_add_f32_e32 v186, 1.0, v186
	v_add_f32_e32 v187, 1.0, v187
	v_rcp_f32_e32 v186, v186
	v_rcp_f32_e32 v187, v187
	v_lshlrev_b64 v[184:185], 11, v[184:185]
	v_pk_mul_f32 v[42:43], v[42:43], v[0:1] op_sel_hi:[1,0]
	v_pk_mul_f32 v[44:45], v[44:45], v[0:1] op_sel_hi:[1,0]
	v_pk_mul_f32 v[46:47], v[46:47], v[186:187]
	v_mul_f32_e32 v186, 0xbfb8aa3b, v48
	v_mul_f32_e32 v187, 0xbfb8aa3b, v49
	v_exp_f32_e32 v186, v186
	v_exp_f32_e32 v187, v187
	v_cvt_pk_bf16_f32 v46, v46, v47
	v_pk_fma_f32 v[42:43], v[10:11], v[42:43], v[14:15]
	v_add_f32_e32 v186, 1.0, v186
	v_add_f32_e32 v187, 1.0, v187
	v_rcp_f32_e32 v186, v186
	v_rcp_f32_e32 v187, v187
	v_pk_fma_f32 v[44:45], v[12:13], v[44:45], v[16:17]
	v_pk_mul_f32 v[38:39], v[38:39], v[0:1] op_sel_hi:[1,0]
	v_pk_mul_f32 v[40:41], v[40:41], v[0:1] op_sel_hi:[1,0]
	v_pk_mul_f32 v[48:49], v[48:49], v[186:187]
	v_pk_fma_f32 v[38:39], v[26:27], v[38:39], v[30:31]
	v_cvt_pk_bf16_f32 v47, v48, v49
	v_lshl_add_u64 v[48:49], v[118:119], 0, v[184:185]
	global_store_dwordx2 v[48:49], v[46:47], off
	v_mul_f32_e32 v46, 0xbfb8aa3b, v42
	v_mul_f32_e32 v47, 0xbfb8aa3b, v43
	v_exp_f32_e32 v46, v46
	v_exp_f32_e32 v47, v47
	v_pk_fma_f32 v[40:41], v[28:29], v[40:41], v[32:33]
	v_pk_mul_f32 v[34:35], v[34:35], v[0:1] op_sel_hi:[1,0]
	v_add_f32_e32 v46, 1.0, v46
	v_add_f32_e32 v47, 1.0, v47
	v_rcp_f32_e32 v46, v46
	v_rcp_f32_e32 v47, v47
	v_pk_fma_f32 v[34:35], v[18:19], v[34:35], v[22:23]
	v_pk_mul_f32 v[36:37], v[36:37], v[0:1] op_sel_hi:[1,0]
	v_mul_f32_e32 v0, 0xbfb8aa3b, v34
	v_pk_mul_f32 v[42:43], v[42:43], v[46:47]
	v_mul_f32_e32 v46, 0xbfb8aa3b, v44
	v_mul_f32_e32 v47, 0xbfb8aa3b, v45
	v_exp_f32_e32 v46, v46
	v_exp_f32_e32 v47, v47
	v_cvt_pk_bf16_f32 v42, v42, v43
	v_exp_f32_e32 v0, v0
	v_add_f32_e32 v46, 1.0, v46
	v_add_f32_e32 v47, 1.0, v47
	v_rcp_f32_e32 v46, v46
	v_rcp_f32_e32 v47, v47
	v_add_f32_e32 v0, 1.0, v0
	v_pk_fma_f32 v[36:37], v[20:21], v[36:37], v[24:25]
	v_pk_mul_f32 v[44:45], v[44:45], v[46:47]
	s_nop 0
	v_cvt_pk_bf16_f32 v43, v44, v45
	global_store_dwordx2 v[48:49], v[42:43], off offset:512
	v_mul_f32_e32 v42, 0xbfb8aa3b, v38
	v_mul_f32_e32 v43, 0xbfb8aa3b, v39
	v_exp_f32_e32 v42, v42
	v_exp_f32_e32 v43, v43
	v_add_f32_e32 v42, 1.0, v42
	v_add_f32_e32 v43, 1.0, v43
	v_rcp_f32_e32 v42, v42
	v_rcp_f32_e32 v43, v43
	s_nop 0
	v_pk_mul_f32 v[38:39], v[38:39], v[42:43]
	v_mul_f32_e32 v42, 0xbfb8aa3b, v40
	v_mul_f32_e32 v43, 0xbfb8aa3b, v41
	v_exp_f32_e32 v42, v42
	v_exp_f32_e32 v43, v43
	v_cvt_pk_bf16_f32 v38, v38, v39
	v_add_f32_e32 v42, 1.0, v42
	v_add_f32_e32 v43, 1.0, v43
	v_rcp_f32_e32 v42, v42
	v_rcp_f32_e32 v43, v43
	s_nop 0
	v_pk_mul_f32 v[40:41], v[40:41], v[42:43]
	s_nop 0
	v_cvt_pk_bf16_f32 v39, v40, v41
	global_store_dwordx2 v[48:49], v[38:39], off offset:1024
	v_rcp_f32_e32 v38, v0
	v_mul_f32_e32 v0, 0xbfb8aa3b, v35
	v_exp_f32_e32 v0, v0
	ds_read_b128 v[42:45], v219 offset:1024
	v_add_f32_e32 v0, 1.0, v0
	v_rcp_f32_e32 v39, v0
	v_mul_f32_e32 v0, 0xbfb8aa3b, v36
	v_exp_f32_e32 v0, v0
	v_pk_mul_f32 v[34:35], v[34:35], v[38:39]
	s_nop 0
	v_cvt_pk_bf16_f32 v34, v34, v35
	v_add_f32_e32 v0, 1.0, v0
	v_rcp_f32_e32 v38, v0
	v_mul_f32_e32 v0, 0xbfb8aa3b, v37
	v_exp_f32_e32 v0, v0
	s_nop 0
	v_add_f32_e32 v0, 1.0, v0
	v_rcp_f32_e32 v39, v0
	s_nop 0
	v_pk_mul_f32 v[36:37], v[36:37], v[38:39]
	s_nop 0
	v_cvt_pk_bf16_f32 v35, v36, v37
	global_store_dwordx2 v[48:49], v[34:35], off offset:1536
	ds_read_b128 v[46:49], v219
	ds_read_b128 v[38:41], v219 offset:2048
	s_waitcnt lgkmcnt(1)
	v_mov_b32_e32 v34, v47
	v_mov_b32_e32 v35, v48
	v_mov_b32_e32 v36, v46
	v_mov_b32_e32 v37, v49
	v_pk_add_f32 v[34:35], v[34:35], v[36:37]
	v_mov_b32_e32 v36, v42
	v_add_f32_e32 v0, v34, v35
	v_mov_b32_e32 v34, v43
	v_mov_b32_e32 v35, v44
	v_mov_b32_e32 v37, v45
	v_pk_add_f32 v[34:35], v[34:35], v[36:37]
	v_add_f32_e32 v184, 0, v0
	v_pk_add_f32 v[186:187], v[34:35], v[34:35] op_sel:[0,1] op_sel_hi:[1,0]
	ds_read_b128 v[34:37], v219 offset:3072
	s_waitcnt lgkmcnt(1)
	v_add_f32_e32 v222, v38, v39
	v_add_f32_e32 v224, v40, v41
	s_waitcnt lgkmcnt(0)
	v_mov_b32_e32 v185, v34
	v_mov_b32_e32 v187, v35
	v_mov_b32_e32 v223, v36
	v_mov_b32_e32 v225, v37
	v_pk_add_f32 v[184:185], v[184:185], v[186:187]
	v_pk_add_f32 v[186:187], v[222:223], v[224:225]
	s_nop 0
	v_pk_add_f32 v[184:185], v[184:185], v[186:187]
	s_nop 0
	v_add_f32_e32 v0, v184, v185
	s_nop 1
	v_add_f32_dpp v184, v0, v0 quad_perm:[1,0,3,2] row_mask:0xf bank_mask:0xf
	s_nop 1
	v_add_f32_dpp v0, v184, v184 quad_perm:[2,3,0,1] row_mask:0xf bank_mask:0xf
	s_nop 1
	v_add_f32_dpp v184, v0, v0 row_half_mirror row_mask:0xf bank_mask:0xf
	s_nop 1
	v_add_f32_dpp v0, v184, v184 row_ror:8 row_mask:0xf bank_mask:0xf
	v_mov_b32_e32 v184, v0
	s_nop 1
	v_permlane16_swap_b32_e32 v184, v0
	v_add_f32_e32 v0, v184, v0
	v_mov_b32_e32 v184, v0
	s_nop 1
	v_permlane32_swap_b32_e32 v184, v0
	v_add_f32_e32 v221, v184, v0
	v_fmamk_f32 v47, v221, 0xba800000, v47
	v_fmamk_f32 v46, v221, 0xba800000, v46
	v_fmamk_f32 v49, v221, 0xba800000, v49
	v_fmac_f32_e32 v48, 0xba800000, v221
	v_pk_mul_f32 v[184:185], v[48:49], v[48:49]
	v_pk_mul_f32 v[186:187], v[46:47], v[46:47]
	v_fmamk_f32 v43, v221, 0xba800000, v43
	v_pk_mov_b32 v[222:223], v[186:187], v[184:185] op_sel:[1,0]
	v_mov_b32_e32 v187, v185
	v_fmamk_f32 v42, v221, 0xba800000, v42
	v_fmamk_f32 v45, v221, 0xba800000, v45
	v_fmac_f32_e32 v44, 0xba800000, v221
	v_pk_add_f32 v[184:185], v[222:223], v[186:187]
	v_pk_mul_f32 v[186:187], v[44:45], v[44:45]
	v_pk_mul_f32 v[222:223], v[42:43], v[42:43]
	v_fmamk_f32 v38, v221, 0xba800000, v38
	v_pk_mov_b32 v[224:225], v[222:223], v[186:187] op_sel:[1,0]
	v_mov_b32_e32 v223, v187
	v_fmamk_f32 v39, v221, 0xba800000, v39
	v_fmac_f32_e32 v40, 0xba800000, v221
	v_mul_f32_e32 v0, v38, v38
	v_pk_add_f32 v[186:187], v[224:225], v[222:223]
	v_fmamk_f32 v41, v221, 0xba800000, v41
	v_pk_fma_f32 v[222:223], v[38:39], v[38:39], v[0:1] op_sel_hi:[1,1,0]
	v_mul_f32_e32 v0, v40, v40
	v_pk_add_f32 v[184:185], v[184:185], v[184:185] op_sel_hi:[0,1]
	v_pk_add_f32 v[186:187], v[186:187], v[186:187] op_sel_hi:[0,1]
	v_pk_fma_f32 v[224:225], v[40:41], v[40:41], v[0:1] op_sel_hi:[1,1,0]
	v_fmamk_f32 v37, v221, 0xba800000, v37
	v_fmamk_f32 v36, v221, 0xba800000, v36
	v_fmamk_f32 v35, v221, 0xba800000, v35
	v_fmac_f32_e32 v34, 0xba800000, v221
	v_mul_f32_e32 v222, v34, v34
	v_mul_f32_e32 v224, v35, v35
	v_mul_f32_e32 v184, v36, v36
	v_mul_f32_e32 v186, v37, v37
	v_pk_add_f32 v[222:223], v[222:223], v[224:225]
	v_pk_add_f32 v[184:185], v[184:185], v[186:187]
	s_nop 0
	v_pk_add_f32 v[184:185], v[222:223], v[184:185]
	s_nop 0
	v_add_f32_e32 v0, v184, v185
	s_nop 1
	v_add_f32_dpp v184, v0, v0 quad_perm:[1,0,3,2] row_mask:0xf bank_mask:0xf
	s_nop 1
	v_add_f32_dpp v0, v184, v184 quad_perm:[2,3,0,1] row_mask:0xf bank_mask:0xf
	s_nop 1
	v_add_f32_dpp v184, v0, v0 row_half_mirror row_mask:0xf bank_mask:0xf
	s_nop 1
	v_add_f32_dpp v0, v184, v184 row_ror:8 row_mask:0xf bank_mask:0xf
	v_mov_b32_e32 v184, v0
	s_nop 1
	v_permlane16_swap_b32_e32 v184, v0
	v_add_f32_e32 v0, v184, v0
	v_mov_b32_e32 v184, v0
	s_nop 1
	v_permlane32_swap_b32_e32 v184, v0
	v_add_f32_e32 v0, v184, v0
	v_fmamk_f32 v0, v0, 0x3a800000, v226
	v_cmp_gt_f32_e32 vcc, s31, v0
	v_mul_f32_e32 v184, 0x4f800000, v0
	s_nop 0
	v_cndmask_b32_e32 v0, v0, v184, vcc
	v_sqrt_f32_e32 v184, v0
	s_nop 0
	v_add_u32_e32 v185, -1, v184
	v_fma_f32 v186, -v185, v184, v0
	v_cmp_ge_f32_e64 s[42:43], 0, v186
	v_add_u32_e32 v186, 1, v184
	s_nop 0
	v_cndmask_b32_e64 v185, v184, v185, s[42:43]
	v_fma_f32 v184, -v186, v184, v0
	v_cmp_lt_f32_e64 s[42:43], 0, v184
	s_nop 1
	v_cndmask_b32_e64 v184, v185, v186, s[42:43]
	v_mul_f32_e32 v185, 0x37800000, v184
	v_cndmask_b32_e32 v184, v184, v185, vcc
	v_cmp_class_f32_e32 vcc, v0, v241
	s_nop 1
	v_cndmask_b32_e32 v0, v184, v0, vcc
	v_div_scale_f32 v184, s[0:1], v0, v0, 1.0
	v_rcp_f32_e32 v185, v184
	s_nop 0
	v_fma_f32 v186, -v184, v185, 1.0
	v_fmac_f32_e32 v185, v186, v185
	v_div_scale_f32 v186, vcc, 1.0, v0, 1.0
	v_mul_f32_e32 v187, v186, v185
	v_fma_f32 v221, -v184, v187, v186
	v_fmac_f32_e32 v187, v221, v185
	v_fma_f32 v184, -v184, v187, v186
	v_div_fmas_f32 v184, v184, v185, v187
	v_div_fixup_f32 v0, v184, v0, 1.0
	v_pk_mul_f32 v[46:47], v[46:47], v[0:1] op_sel_hi:[1,0]
	v_pk_mul_f32 v[48:49], v[48:49], v[0:1] op_sel_hi:[1,0]
	v_pk_fma_f32 v[46:47], v[2:3], v[46:47], v[6:7]
	v_pk_fma_f32 v[48:49], v[4:5], v[48:49], v[8:9]
	v_mul_f32_e32 v186, 0xbfb8aa3b, v46
	v_mul_f32_e32 v187, 0xbfb8aa3b, v47
	v_exp_f32_e32 v186, v186
	v_exp_f32_e32 v187, v187
	v_add_u32_e32 v184, s9, v215
	v_ashrrev_i32_e32 v185, 31, v184
	v_add_f32_e32 v186, 1.0, v186
	v_add_f32_e32 v187, 1.0, v187
	v_rcp_f32_e32 v186, v186
	v_rcp_f32_e32 v187, v187
	v_lshlrev_b64 v[184:185], 11, v[184:185]
	v_pk_mul_f32 v[42:43], v[42:43], v[0:1] op_sel_hi:[1,0]
	v_pk_mul_f32 v[44:45], v[44:45], v[0:1] op_sel_hi:[1,0]
	v_pk_mul_f32 v[46:47], v[46:47], v[186:187]
	v_mul_f32_e32 v186, 0xbfb8aa3b, v48
	v_mul_f32_e32 v187, 0xbfb8aa3b, v49
	v_exp_f32_e32 v186, v186
	v_exp_f32_e32 v187, v187
	v_cvt_pk_bf16_f32 v46, v46, v47
	v_pk_fma_f32 v[42:43], v[10:11], v[42:43], v[14:15]
	v_add_f32_e32 v186, 1.0, v186
	v_add_f32_e32 v187, 1.0, v187
	v_rcp_f32_e32 v186, v186
	v_rcp_f32_e32 v187, v187
	v_pk_fma_f32 v[44:45], v[12:13], v[44:45], v[16:17]
	v_pk_mul_f32 v[38:39], v[38:39], v[0:1] op_sel_hi:[1,0]
	v_pk_mul_f32 v[40:41], v[40:41], v[0:1] op_sel_hi:[1,0]
	v_pk_mul_f32 v[48:49], v[48:49], v[186:187]
	v_pk_fma_f32 v[38:39], v[26:27], v[38:39], v[30:31]
	v_cvt_pk_bf16_f32 v47, v48, v49
	v_lshl_add_u64 v[48:49], v[118:119], 0, v[184:185]
	global_store_dwordx2 v[48:49], v[46:47], off
	v_mul_f32_e32 v46, 0xbfb8aa3b, v42
	v_mul_f32_e32 v47, 0xbfb8aa3b, v43
	v_exp_f32_e32 v46, v46
	v_exp_f32_e32 v47, v47
	v_pk_fma_f32 v[40:41], v[28:29], v[40:41], v[32:33]
	v_pk_mul_f32 v[34:35], v[34:35], v[0:1] op_sel_hi:[1,0]
	v_add_f32_e32 v46, 1.0, v46
	v_add_f32_e32 v47, 1.0, v47
	v_rcp_f32_e32 v46, v46
	v_rcp_f32_e32 v47, v47
	v_pk_fma_f32 v[34:35], v[18:19], v[34:35], v[22:23]
	v_pk_mul_f32 v[36:37], v[36:37], v[0:1] op_sel_hi:[1,0]
	v_mul_f32_e32 v0, 0xbfb8aa3b, v34
	v_pk_mul_f32 v[42:43], v[42:43], v[46:47]
	v_mul_f32_e32 v46, 0xbfb8aa3b, v44
	v_mul_f32_e32 v47, 0xbfb8aa3b, v45
	v_exp_f32_e32 v46, v46
	v_exp_f32_e32 v47, v47
	v_cvt_pk_bf16_f32 v42, v42, v43
	v_exp_f32_e32 v0, v0
	v_add_f32_e32 v46, 1.0, v46
	v_add_f32_e32 v47, 1.0, v47
	v_rcp_f32_e32 v46, v46
	v_rcp_f32_e32 v47, v47
	v_add_f32_e32 v0, 1.0, v0
	v_pk_fma_f32 v[36:37], v[20:21], v[36:37], v[24:25]
	v_pk_mul_f32 v[44:45], v[44:45], v[46:47]
	s_nop 0
	v_cvt_pk_bf16_f32 v43, v44, v45
	global_store_dwordx2 v[48:49], v[42:43], off offset:512
	v_mul_f32_e32 v42, 0xbfb8aa3b, v38
	v_mul_f32_e32 v43, 0xbfb8aa3b, v39
	v_exp_f32_e32 v42, v42
	v_exp_f32_e32 v43, v43
	v_add_f32_e32 v42, 1.0, v42
	v_add_f32_e32 v43, 1.0, v43
	v_rcp_f32_e32 v42, v42
	v_rcp_f32_e32 v43, v43
	s_nop 0
	v_pk_mul_f32 v[38:39], v[38:39], v[42:43]
	v_mul_f32_e32 v42, 0xbfb8aa3b, v40
	v_mul_f32_e32 v43, 0xbfb8aa3b, v41
	v_exp_f32_e32 v42, v42
	v_exp_f32_e32 v43, v43
	v_cvt_pk_bf16_f32 v38, v38, v39
	v_add_f32_e32 v42, 1.0, v42
	v_add_f32_e32 v43, 1.0, v43
	v_rcp_f32_e32 v42, v42
	v_rcp_f32_e32 v43, v43
	s_nop 0
	v_pk_mul_f32 v[40:41], v[40:41], v[42:43]
	s_nop 0
	v_cvt_pk_bf16_f32 v39, v40, v41
	global_store_dwordx2 v[48:49], v[38:39], off offset:1024
	v_rcp_f32_e32 v38, v0
	v_mul_f32_e32 v0, 0xbfb8aa3b, v35
	v_exp_f32_e32 v0, v0
	ds_read_b128 v[42:45], v220 offset:1024
	v_add_f32_e32 v0, 1.0, v0
	v_rcp_f32_e32 v39, v0
	v_mul_f32_e32 v0, 0xbfb8aa3b, v36
	v_exp_f32_e32 v0, v0
	v_pk_mul_f32 v[34:35], v[34:35], v[38:39]
	s_nop 0
	v_cvt_pk_bf16_f32 v34, v34, v35
	v_add_f32_e32 v0, 1.0, v0
	v_rcp_f32_e32 v38, v0
	v_mul_f32_e32 v0, 0xbfb8aa3b, v37
	v_exp_f32_e32 v0, v0
	s_nop 0
	v_add_f32_e32 v0, 1.0, v0
	v_rcp_f32_e32 v39, v0
	s_nop 0
	v_pk_mul_f32 v[36:37], v[36:37], v[38:39]
	s_nop 0
	v_cvt_pk_bf16_f32 v35, v36, v37
	global_store_dwordx2 v[48:49], v[34:35], off offset:1536
	ds_read_b128 v[46:49], v220
	ds_read_b128 v[38:41], v220 offset:2048
	s_waitcnt lgkmcnt(1)
	v_mov_b32_e32 v34, v47
	v_mov_b32_e32 v35, v48
	v_mov_b32_e32 v36, v46
	v_mov_b32_e32 v37, v49
	v_pk_add_f32 v[34:35], v[34:35], v[36:37]
	v_mov_b32_e32 v36, v42
	v_add_f32_e32 v0, v34, v35
	v_mov_b32_e32 v34, v43
	v_mov_b32_e32 v35, v44
	v_mov_b32_e32 v37, v45
	v_pk_add_f32 v[34:35], v[34:35], v[36:37]
	v_add_f32_e32 v184, 0, v0
	v_pk_add_f32 v[186:187], v[34:35], v[34:35] op_sel:[0,1] op_sel_hi:[1,0]
	ds_read_b128 v[34:37], v220 offset:3072
	s_waitcnt lgkmcnt(1)
	v_add_f32_e32 v222, v38, v39
	v_add_f32_e32 v224, v40, v41
	s_waitcnt lgkmcnt(0)
	v_mov_b32_e32 v185, v34
	v_mov_b32_e32 v187, v35
	v_mov_b32_e32 v223, v36
	v_mov_b32_e32 v225, v37
	v_pk_add_f32 v[184:185], v[184:185], v[186:187]
	v_pk_add_f32 v[186:187], v[222:223], v[224:225]
	s_nop 0
	v_pk_add_f32 v[184:185], v[184:185], v[186:187]
	s_nop 0
	v_add_f32_e32 v0, v184, v185
	s_nop 1
	v_add_f32_dpp v184, v0, v0 quad_perm:[1,0,3,2] row_mask:0xf bank_mask:0xf
	s_nop 1
	v_add_f32_dpp v0, v184, v184 quad_perm:[2,3,0,1] row_mask:0xf bank_mask:0xf
	s_nop 1
	v_add_f32_dpp v184, v0, v0 row_half_mirror row_mask:0xf bank_mask:0xf
	s_nop 1
	v_add_f32_dpp v0, v184, v184 row_ror:8 row_mask:0xf bank_mask:0xf
	v_mov_b32_e32 v184, v0
	s_nop 1
	v_permlane16_swap_b32_e32 v184, v0
	v_add_f32_e32 v0, v184, v0
	v_mov_b32_e32 v184, v0
	s_nop 1
	v_permlane32_swap_b32_e32 v184, v0
	v_add_f32_e32 v221, v184, v0
	v_fmamk_f32 v47, v221, 0xba800000, v47
	v_fmamk_f32 v46, v221, 0xba800000, v46
	v_fmamk_f32 v49, v221, 0xba800000, v49
	v_fmac_f32_e32 v48, 0xba800000, v221
	v_pk_mul_f32 v[184:185], v[48:49], v[48:49]
	v_pk_mul_f32 v[186:187], v[46:47], v[46:47]
	v_fmamk_f32 v43, v221, 0xba800000, v43
	v_pk_mov_b32 v[222:223], v[186:187], v[184:185] op_sel:[1,0]
	v_mov_b32_e32 v187, v185
	v_fmamk_f32 v42, v221, 0xba800000, v42
	v_fmamk_f32 v45, v221, 0xba800000, v45
	v_fmac_f32_e32 v44, 0xba800000, v221
	v_pk_add_f32 v[184:185], v[222:223], v[186:187]
	v_pk_mul_f32 v[186:187], v[44:45], v[44:45]
	v_pk_mul_f32 v[222:223], v[42:43], v[42:43]
	v_fmamk_f32 v38, v221, 0xba800000, v38
	v_pk_mov_b32 v[224:225], v[222:223], v[186:187] op_sel:[1,0]
	v_mov_b32_e32 v223, v187
	v_fmamk_f32 v39, v221, 0xba800000, v39
	v_fmac_f32_e32 v40, 0xba800000, v221
	v_mul_f32_e32 v0, v38, v38
	v_pk_add_f32 v[186:187], v[224:225], v[222:223]
	v_fmamk_f32 v41, v221, 0xba800000, v41
	v_pk_fma_f32 v[222:223], v[38:39], v[38:39], v[0:1] op_sel_hi:[1,1,0]
	v_mul_f32_e32 v0, v40, v40
	v_pk_add_f32 v[184:185], v[184:185], v[184:185] op_sel_hi:[0,1]
	v_pk_add_f32 v[186:187], v[186:187], v[186:187] op_sel_hi:[0,1]
	v_pk_fma_f32 v[224:225], v[40:41], v[40:41], v[0:1] op_sel_hi:[1,1,0]
	v_fmamk_f32 v37, v221, 0xba800000, v37
	v_fmamk_f32 v36, v221, 0xba800000, v36
	v_fmamk_f32 v35, v221, 0xba800000, v35
	v_fmac_f32_e32 v34, 0xba800000, v221
	v_mul_f32_e32 v222, v34, v34
	v_mul_f32_e32 v224, v35, v35
	v_mul_f32_e32 v184, v36, v36
	v_mul_f32_e32 v186, v37, v37
	v_pk_add_f32 v[222:223], v[222:223], v[224:225]
	v_pk_add_f32 v[184:185], v[184:185], v[186:187]
	s_nop 0
	v_pk_add_f32 v[184:185], v[222:223], v[184:185]
	s_nop 0
	v_add_f32_e32 v0, v184, v185
	s_nop 1
	v_add_f32_dpp v184, v0, v0 quad_perm:[1,0,3,2] row_mask:0xf bank_mask:0xf
	s_nop 1
	v_add_f32_dpp v0, v184, v184 quad_perm:[2,3,0,1] row_mask:0xf bank_mask:0xf
	s_nop 1
	v_add_f32_dpp v184, v0, v0 row_half_mirror row_mask:0xf bank_mask:0xf
	s_nop 1
	v_add_f32_dpp v0, v184, v184 row_ror:8 row_mask:0xf bank_mask:0xf
	v_mov_b32_e32 v184, v0
	s_nop 1
	v_permlane16_swap_b32_e32 v184, v0
	v_add_f32_e32 v0, v184, v0
	v_mov_b32_e32 v184, v0
	s_nop 1
	v_permlane32_swap_b32_e32 v184, v0
	v_add_f32_e32 v0, v184, v0
	v_fmamk_f32 v0, v0, 0x3a800000, v226
	v_cmp_gt_f32_e32 vcc, s31, v0
	v_mul_f32_e32 v184, 0x4f800000, v0
	s_nop 0
	v_cndmask_b32_e32 v0, v0, v184, vcc
	v_sqrt_f32_e32 v184, v0
	s_nop 0
	v_add_u32_e32 v185, -1, v184
	v_fma_f32 v186, -v185, v184, v0
	v_cmp_ge_f32_e64 s[42:43], 0, v186
	v_add_u32_e32 v186, 1, v184
	s_nop 0
	v_cndmask_b32_e64 v185, v184, v185, s[42:43]
	v_fma_f32 v184, -v186, v184, v0
	v_cmp_lt_f32_e64 s[42:43], 0, v184
	s_nop 1
	v_cndmask_b32_e64 v184, v185, v186, s[42:43]
	v_mul_f32_e32 v185, 0x37800000, v184
	v_cndmask_b32_e32 v184, v184, v185, vcc
	v_cmp_class_f32_e32 vcc, v0, v241
	s_nop 1
	v_cndmask_b32_e32 v0, v184, v0, vcc
	v_div_scale_f32 v184, s[0:1], v0, v0, 1.0
	v_rcp_f32_e32 v185, v184
	v_readlane_b32 s0, v252, 61
	s_add_i32 s8, s8, s0
	v_readlane_b32 s0, v252, 63
	v_fma_f32 v186, -v184, v185, 1.0
	v_fmac_f32_e32 v185, v186, v185
	v_div_scale_f32 v186, vcc, 1.0, v0, 1.0
	v_mul_f32_e32 v187, v186, v185
	v_fma_f32 v221, -v184, v187, v186
	v_fmac_f32_e32 v187, v221, v185
	v_fma_f32 v184, -v184, v187, v186
	v_div_fmas_f32 v184, v184, v185, v187
	v_div_fixup_f32 v0, v184, v0, 1.0
	v_pk_mul_f32 v[46:47], v[46:47], v[0:1] op_sel_hi:[1,0]
	v_pk_mul_f32 v[48:49], v[48:49], v[0:1] op_sel_hi:[1,0]
	v_pk_fma_f32 v[2:3], v[2:3], v[46:47], v[6:7]
	v_pk_fma_f32 v[4:5], v[4:5], v[48:49], v[8:9]
	v_mul_f32_e32 v6, 0xbfb8aa3b, v2
	v_mul_f32_e32 v7, 0xbfb8aa3b, v3
	v_exp_f32_e32 v6, v6
	v_exp_f32_e32 v7, v7
	v_add_u32_e32 v184, s9, v216
	v_ashrrev_i32_e32 v185, 31, v184
	v_add_f32_e32 v6, 1.0, v6
	v_add_f32_e32 v7, 1.0, v7
	v_rcp_f32_e32 v6, v6
	v_rcp_f32_e32 v7, v7
	v_lshlrev_b64 v[184:185], 11, v[184:185]
	s_cmp_ge_i32 s8, s0
	v_pk_mul_f32 v[2:3], v[2:3], v[6:7]
	v_mul_f32_e32 v6, 0xbfb8aa3b, v4
	v_mul_f32_e32 v7, 0xbfb8aa3b, v5
	v_exp_f32_e32 v6, v6
	v_exp_f32_e32 v7, v7
	v_add_f32_e32 v6, 1.0, v6
	v_add_f32_e32 v7, 1.0, v7
	v_rcp_f32_e32 v6, v6
	v_rcp_f32_e32 v7, v7
	s_nop 0
	v_pk_mul_f32 v[4:5], v[4:5], v[6:7]
	s_nop 0
	v_cvt_pk_bf16_f32 v7, v4, v5
	v_pk_mul_f32 v[4:5], v[42:43], v[0:1] op_sel_hi:[1,0]
	v_cvt_pk_bf16_f32 v6, v2, v3
	v_pk_fma_f32 v[4:5], v[10:11], v[4:5], v[14:15]
	v_lshl_add_u64 v[2:3], v[118:119], 0, v[184:185]
	v_mul_f32_e32 v8, 0xbfb8aa3b, v4
	v_mul_f32_e32 v9, 0xbfb8aa3b, v5
	v_exp_f32_e32 v8, v8
	v_exp_f32_e32 v9, v9
	global_store_dwordx2 v[2:3], v[6:7], off
	v_pk_mul_f32 v[6:7], v[44:45], v[0:1] op_sel_hi:[1,0]
	v_add_f32_e32 v8, 1.0, v8
	v_add_f32_e32 v9, 1.0, v9
	v_rcp_f32_e32 v8, v8
	v_rcp_f32_e32 v9, v9
	v_pk_fma_f32 v[6:7], v[12:13], v[6:7], v[16:17]
	v_pk_mul_f32 v[4:5], v[4:5], v[8:9]
	v_mul_f32_e32 v8, 0xbfb8aa3b, v6
	v_mul_f32_e32 v9, 0xbfb8aa3b, v7
	v_exp_f32_e32 v8, v8
	v_exp_f32_e32 v9, v9
	v_cvt_pk_bf16_f32 v4, v4, v5
	v_add_f32_e32 v8, 1.0, v8
	v_add_f32_e32 v9, 1.0, v9
	v_rcp_f32_e32 v8, v8
	v_rcp_f32_e32 v9, v9
	s_nop 0
	v_pk_mul_f32 v[6:7], v[6:7], v[8:9]
	s_nop 0
	v_cvt_pk_bf16_f32 v5, v6, v7
	global_store_dwordx2 v[2:3], v[4:5], off offset:512
	v_pk_mul_f32 v[4:5], v[38:39], v[0:1] op_sel_hi:[1,0]
	v_pk_mul_f32 v[6:7], v[40:41], v[0:1] op_sel_hi:[1,0]
	v_pk_fma_f32 v[4:5], v[26:27], v[4:5], v[30:31]
	v_pk_fma_f32 v[6:7], v[28:29], v[6:7], v[32:33]
	v_mul_f32_e32 v8, 0xbfb8aa3b, v4
	v_mul_f32_e32 v9, 0xbfb8aa3b, v5
	v_exp_f32_e32 v8, v8
	v_exp_f32_e32 v9, v9
	v_add_f32_e32 v8, 1.0, v8
	v_add_f32_e32 v9, 1.0, v9
	v_rcp_f32_e32 v8, v8
	v_rcp_f32_e32 v9, v9
	s_nop 0
	v_pk_mul_f32 v[4:5], v[4:5], v[8:9]
	v_mul_f32_e32 v8, 0xbfb8aa3b, v6
	v_mul_f32_e32 v9, 0xbfb8aa3b, v7
	v_exp_f32_e32 v8, v8
	v_exp_f32_e32 v9, v9
	v_cvt_pk_bf16_f32 v4, v4, v5
	v_add_f32_e32 v8, 1.0, v8
	v_add_f32_e32 v9, 1.0, v9
	v_rcp_f32_e32 v8, v8
	v_rcp_f32_e32 v9, v9
	s_nop 0
	v_pk_mul_f32 v[6:7], v[6:7], v[8:9]
	s_nop 0
	v_cvt_pk_bf16_f32 v5, v6, v7
	global_store_dwordx2 v[2:3], v[4:5], off offset:1024
	v_pk_mul_f32 v[4:5], v[34:35], v[0:1] op_sel_hi:[1,0]
	v_pk_mul_f32 v[6:7], v[36:37], v[0:1] op_sel_hi:[1,0]
	v_pk_fma_f32 v[4:5], v[18:19], v[4:5], v[22:23]
	v_pk_fma_f32 v[6:7], v[20:21], v[6:7], v[24:25]
	v_mul_f32_e32 v0, 0xbfb8aa3b, v4
	v_exp_f32_e32 v0, v0
	s_nop 0
	v_add_f32_e32 v0, 1.0, v0
	v_rcp_f32_e32 v8, v0
	v_mul_f32_e32 v0, 0xbfb8aa3b, v5
	v_exp_f32_e32 v0, v0
	s_nop 0
	v_add_f32_e32 v0, 1.0, v0
	v_rcp_f32_e32 v9, v0
	v_mul_f32_e32 v0, 0xbfb8aa3b, v6
	v_exp_f32_e32 v0, v0
	v_pk_mul_f32 v[4:5], v[4:5], v[8:9]
	s_nop 0
	v_cvt_pk_bf16_f32 v4, v4, v5
	v_add_f32_e32 v0, 1.0, v0
	v_rcp_f32_e32 v8, v0
	v_mul_f32_e32 v0, 0xbfb8aa3b, v7
	v_exp_f32_e32 v0, v0
	s_nop 0
	v_add_f32_e32 v0, 1.0, v0
	v_rcp_f32_e32 v9, v0
	s_nop 0
	v_pk_mul_f32 v[6:7], v[6:7], v[8:9]
	s_nop 0
	v_cvt_pk_bf16_f32 v5, v6, v7
	global_store_dwordx2 v[2:3], v[4:5], off offset:1536
	s_barrier
	s_cbranch_scc1 .LBB0_729
